# v8 + G3 projection stores sc0 sc1 nt
# baseline (speedup 1.0000x reference)
.LBB0_347:
	s_ashr_i32 s15, s14, 31
	s_lshl_b64 s[12:13], s[14:15], 25
	v_ashrrev_i32_e32 v225, 31, v224
	s_add_u32 s24, s41, s12
	s_addc_u32 s25, s42, s13
	v_lshlrev_b64 v[146:147], 9, v[224:225]
	v_mov_b64_e32 v[94:95], v[2:3]
	v_lshl_add_u64 v[146:147], s[24:25], 0, v[146:147]
	v_lshlrev_b32_e32 v2, 1, v214
	v_lshl_add_u64 v[146:147], v[146:147], 0, v[2:3]
	global_store_dwordx4 v[146:147], v[142:145], off sc0 sc1 nt
	v_cndmask_b32_e64 v149, 0, 1, s[26:27]
	v_cmp_ne_u32_e64 s[12:13], 1, v149
	v_mov_b32_e32 v143, v128
	v_mov_b32_e32 v128, v137
	v_mov_b32_e32 v142, v136
	v_pk_mul_f32 v[136:137], v[128:129], v[192:193]
	s_andn2_b64 vcc, exec, s[26:27]
	v_pk_fma_f32 v[136:137], v[142:143], v[188:189], v[136:137] neg_lo:[0,0,1] neg_hi:[0,0,1]
	v_pk_mul_f32 v[142:143], v[142:143], v[192:193]
	s_nop 0
	v_pk_fma_f32 v[142:143], v[128:129], v[188:189], v[142:143]
	v_mov_b32_e32 v129, v130
	v_mov_b32_e32 v130, v139
	v_mov_b32_e32 v128, v138
	v_pk_mul_f32 v[138:139], v[130:131], v[178:179]
	s_nop 0
	v_pk_fma_f32 v[138:139], v[128:129], v[238:239], v[138:139] neg_lo:[0,0,1] neg_hi:[0,0,1]
	v_pk_mul_f32 v[128:129], v[128:129], v[178:179]
	s_nop 0
	v_pk_fma_f32 v[144:145], v[130:131], v[238:239], v[128:129]
	v_mul_f32_e32 v128, v186, v136
	v_mul_f32_e32 v129, v186, v142
	v_cvt_pk_bf16_f32 v128, v128, v129
	v_mul_f32_e32 v129, v186, v138
	v_mul_f32_e32 v130, v186, v144
	v_cvt_pk_bf16_f32 v129, v129, v130
	v_mul_f32_e32 v130, v186, v137
	v_mul_f32_e32 v131, v186, v143
	v_cvt_pk_bf16_f32 v130, v130, v131
	v_mul_f32_e32 v131, v186, v139
	v_mul_f32_e32 v148, v186, v145
	v_cvt_pk_bf16_f32 v131, v131, v148
	s_cbranch_vccnz .LBB0_349
	v_pk_mul_f32 v[142:143], v[142:143], v[142:143]
	v_pk_mul_f32 v[144:145], v[144:145], v[144:145]
	v_pk_fma_f32 v[136:137], v[136:137], v[136:137], v[142:143]
	v_pk_fma_f32 v[138:139], v[138:139], v[138:139], v[144:145]
	v_max_f32_e32 v95, v95, v95
	v_pk_add_f32 v[136:137], v[136:137], v[138:139]
	s_nop 0
	v_add_f32_e32 v136, v136, v137
	ds_swizzle_b32 v137, v136 offset:swizzle(SWAP,16)
	s_waitcnt lgkmcnt(0)
	v_add_f32_e32 v136, v136, v137
	v_mov_b32_e32 v137, v136
	s_nop 1
	v_permlane32_swap_b32_e32 v136, v137
	v_add_f32_e32 v136, v136, v137
	v_max_f32_e32 v95, v95, v136
.LBB0_349:
	global_store_dwordx4 v[146:147], v[128:131], off offset:256 sc0 sc1 nt
	s_and_b64 vcc, exec, s[12:13]
	s_nop 0
	v_mov_b32_e32 v129, v116
	v_mov_b32_e32 v116, v125
	v_mov_b32_e32 v128, v124
	v_pk_mul_f32 v[124:125], v[116:117], v[184:185]
	s_nop 0
	v_pk_fma_f32 v[124:125], v[128:129], v[180:181], v[124:125] neg_lo:[0,0,1] neg_hi:[0,0,1]
	v_pk_mul_f32 v[128:129], v[128:129], v[184:185]
	s_nop 0
	v_pk_fma_f32 v[128:129], v[116:117], v[180:181], v[128:129]
	v_mov_b32_e32 v117, v118
	v_mov_b32_e32 v118, v127
	v_mov_b32_e32 v116, v126
	v_pk_mul_f32 v[126:127], v[118:119], v[98:99]
	s_nop 0
	v_pk_fma_f32 v[126:127], v[116:117], v[236:237], v[126:127] neg_lo:[0,0,1] neg_hi:[0,0,1]
	v_pk_mul_f32 v[116:117], v[116:117], v[98:99]
	s_nop 0
	v_pk_fma_f32 v[130:131], v[118:119], v[236:237], v[116:117]
	v_mul_f32_e32 v116, v186, v124
	v_mul_f32_e32 v117, v186, v128
	v_cvt_pk_bf16_f32 v116, v116, v117
	v_mul_f32_e32 v117, v186, v126
	v_mul_f32_e32 v118, v186, v130
	v_cvt_pk_bf16_f32 v117, v117, v118
	v_mul_f32_e32 v118, v186, v125
	v_mul_f32_e32 v119, v186, v129
	v_cvt_pk_bf16_f32 v118, v118, v119
	v_mul_f32_e32 v119, v186, v127
	v_mul_f32_e32 v136, v186, v131
	v_cvt_pk_bf16_f32 v119, v119, v136
	s_cbranch_vccnz .LBB0_351
	v_pk_mul_f32 v[128:129], v[128:129], v[128:129]
	v_pk_mul_f32 v[130:131], v[130:131], v[130:131]
	v_pk_fma_f32 v[124:125], v[124:125], v[124:125], v[128:129]
	v_pk_fma_f32 v[126:127], v[126:127], v[126:127], v[130:131]
	v_max_f32_e32 v94, v94, v94
	v_pk_add_f32 v[124:125], v[124:125], v[126:127]
	s_nop 0
	v_add_f32_e32 v124, v124, v125
	ds_swizzle_b32 v125, v124 offset:swizzle(SWAP,16)
	s_waitcnt lgkmcnt(0)
	v_add_f32_e32 v124, v124, v125
	v_mov_b32_e32 v125, v124
	s_nop 1
	v_permlane32_swap_b32_e32 v124, v125
	v_add_f32_e32 v124, v124, v125
	v_max_f32_e32 v94, v94, v124
.LBB0_351:
	v_ashrrev_i32_e32 v233, 31, v232
	v_lshlrev_b64 v[124:125], 9, v[232:233]
	v_lshl_add_u64 v[124:125], s[24:25], 0, v[124:125]
	v_lshl_add_u64 v[124:125], v[124:125], 0, v[2:3]
	global_store_dwordx4 v[124:125], v[116:119], off sc0 sc1 nt
	s_and_b64 vcc, exec, s[12:13]
	s_nop 0
	v_mov_b32_e32 v117, v108
	v_mov_b32_e32 v108, v113
	v_mov_b32_e32 v116, v112
	v_pk_mul_f32 v[112:113], v[108:109], v[184:185]
	s_nop 0
	v_pk_fma_f32 v[112:113], v[116:117], v[180:181], v[112:113] neg_lo:[0,0,1] neg_hi:[0,0,1]
	v_pk_mul_f32 v[116:117], v[116:117], v[184:185]
	s_nop 0
	v_pk_fma_f32 v[116:117], v[108:109], v[180:181], v[116:117]
	v_mov_b32_e32 v108, v114
	v_mov_b32_e32 v109, v110
	v_mov_b32_e32 v110, v115
	v_pk_mul_f32 v[114:115], v[110:111], v[98:99]
	v_pk_mul_f32 v[98:99], v[108:109], v[98:99]
	v_pk_fma_f32 v[114:115], v[108:109], v[236:237], v[114:115] neg_lo:[0,0,1] neg_hi:[0,0,1]
	v_pk_fma_f32 v[98:99], v[110:111], v[236:237], v[98:99]
	v_mul_f32_e32 v108, v186, v112
	v_mul_f32_e32 v109, v186, v116
	v_cvt_pk_bf16_f32 v108, v108, v109
	v_mul_f32_e32 v109, v186, v114
	v_mul_f32_e32 v110, v186, v98
	v_cvt_pk_bf16_f32 v109, v109, v110
	v_mul_f32_e32 v110, v186, v113
	v_mul_f32_e32 v111, v186, v117
	v_cvt_pk_bf16_f32 v110, v110, v111
	v_mul_f32_e32 v111, v186, v115
	v_mul_f32_e32 v118, v186, v99
	v_cvt_pk_bf16_f32 v111, v111, v118
	s_cbranch_vccnz .LBB0_353
	v_pk_mul_f32 v[116:117], v[116:117], v[116:117]
	v_pk_mul_f32 v[98:99], v[98:99], v[98:99]
	v_pk_fma_f32 v[112:113], v[112:113], v[112:113], v[116:117]
	v_pk_fma_f32 v[98:99], v[114:115], v[114:115], v[98:99]
	v_max_f32_e32 v95, v95, v95
	v_pk_add_f32 v[98:99], v[112:113], v[98:99]
	s_nop 0
	v_add_f32_e32 v98, v98, v99
	ds_swizzle_b32 v99, v98 offset:swizzle(SWAP,16)
	s_waitcnt lgkmcnt(0)
	v_add_f32_e32 v98, v98, v99
	v_mov_b32_e32 v99, v98
	s_nop 1
	v_permlane32_swap_b32_e32 v98, v99
	v_add_f32_e32 v98, v98, v99
	v_max_f32_e32 v95, v95, v98
.LBB0_353:
	v_mov_b32_e32 v99, v100
	v_mov_b32_e32 v100, v105
	v_mov_b32_e32 v98, v104
	v_pk_mul_f32 v[104:105], v[100:101], v[176:177]
	global_store_dwordx4 v[124:125], v[108:111], off offset:256 sc0 sc1 nt
	v_pk_fma_f32 v[104:105], v[98:99], v[172:173], v[104:105] neg_lo:[0,0,1] neg_hi:[0,0,1]
	v_pk_mul_f32 v[98:99], v[98:99], v[176:177]
	s_and_b64 vcc, exec, s[12:13]
	v_pk_fma_f32 v[108:109], v[100:101], v[172:173], v[98:99]
	v_mov_b32_e32 v99, v102
	v_mov_b32_e32 v102, v107
	v_mov_b32_e32 v98, v106
	v_pk_mul_f32 v[100:101], v[102:103], v[170:171]
	s_nop 0
	v_pk_fma_f32 v[106:107], v[98:99], v[234:235], v[100:101] neg_lo:[0,0,1] neg_hi:[0,0,1]
	v_pk_mul_f32 v[98:99], v[98:99], v[170:171]
	v_mul_f32_e32 v101, v186, v109
	v_pk_fma_f32 v[102:103], v[102:103], v[234:235], v[98:99]
	v_mul_f32_e32 v98, v186, v104
	v_mul_f32_e32 v99, v186, v108
	v_cvt_pk_bf16_f32 v98, v98, v99
	v_mul_f32_e32 v99, v186, v106
	v_mul_f32_e32 v100, v186, v102
	v_cvt_pk_bf16_f32 v99, v99, v100
	v_mul_f32_e32 v100, v186, v105
	v_cvt_pk_bf16_f32 v100, v100, v101
	v_mul_f32_e32 v101, v186, v107
	v_mul_f32_e32 v110, v186, v103
	v_cvt_pk_bf16_f32 v101, v101, v110
	s_cbranch_vccnz .LBB0_355
	v_pk_mul_f32 v[108:109], v[108:109], v[108:109]
	v_pk_mul_f32 v[102:103], v[102:103], v[102:103]
	v_pk_fma_f32 v[104:105], v[104:105], v[104:105], v[108:109]
	v_pk_fma_f32 v[102:103], v[106:107], v[106:107], v[102:103]
	v_max_f32_e32 v94, v94, v94
	v_pk_add_f32 v[102:103], v[104:105], v[102:103]
	s_nop 0
	v_add_f32_e32 v102, v102, v103
	ds_swizzle_b32 v103, v102 offset:swizzle(SWAP,16)
	s_waitcnt lgkmcnt(0)
	v_add_f32_e32 v102, v102, v103
	v_mov_b32_e32 v103, v102
	s_nop 1
	v_permlane32_swap_b32_e32 v102, v103
	v_add_f32_e32 v102, v102, v103
	v_max_f32_e32 v94, v94, v102
.LBB0_355:
	v_ashrrev_i32_e32 v229, 31, v228
	v_lshlrev_b64 v[102:103], 9, v[228:229]
	v_lshl_add_u64 v[102:103], s[24:25], 0, v[102:103]
	v_lshl_add_u64 v[102:103], v[102:103], 0, v[2:3]
	global_store_dwordx4 v[102:103], v[98:101], off sc0 sc1 nt
	s_and_b64 vcc, exec, s[12:13]
	s_nop 0
	v_mov_b32_e32 v99, v84
	v_mov_b32_e32 v84, v89
	v_mov_b32_e32 v98, v88
	v_pk_mul_f32 v[88:89], v[84:85], v[176:177]
	s_nop 0
	v_pk_fma_f32 v[88:89], v[98:99], v[172:173], v[88:89] neg_lo:[0,0,1] neg_hi:[0,0,1]
	v_pk_mul_f32 v[98:99], v[98:99], v[176:177]
	s_nop 0
	v_pk_fma_f32 v[98:99], v[84:85], v[172:173], v[98:99]
	v_mov_b32_e32 v85, v86
	v_mov_b32_e32 v86, v91
	v_mov_b32_e32 v84, v90
	v_pk_mul_f32 v[90:91], v[86:87], v[170:171]
	s_nop 0
	v_pk_fma_f32 v[90:91], v[84:85], v[234:235], v[90:91] neg_lo:[0,0,1] neg_hi:[0,0,1]
	v_pk_mul_f32 v[84:85], v[84:85], v[170:171]
	s_nop 0
	v_pk_fma_f32 v[100:101], v[86:87], v[234:235], v[84:85]
	v_mul_f32_e32 v84, v186, v88
	v_mul_f32_e32 v85, v186, v98
	v_cvt_pk_bf16_f32 v84, v84, v85
	v_mul_f32_e32 v85, v186, v90
	v_mul_f32_e32 v86, v186, v100
	v_cvt_pk_bf16_f32 v85, v85, v86
	v_mul_f32_e32 v86, v186, v89
	v_mul_f32_e32 v87, v186, v99
	v_cvt_pk_bf16_f32 v86, v86, v87
	v_mul_f32_e32 v87, v186, v91
	v_mul_f32_e32 v104, v186, v101
	v_cvt_pk_bf16_f32 v87, v87, v104
	s_cbranch_vccnz .LBB0_357
	v_pk_mul_f32 v[98:99], v[98:99], v[98:99]
	v_pk_mul_f32 v[100:101], v[100:101], v[100:101]
	v_pk_fma_f32 v[88:89], v[88:89], v[88:89], v[98:99]
	v_pk_fma_f32 v[90:91], v[90:91], v[90:91], v[100:101]
	s_nop 0
	v_pk_add_f32 v[88:89], v[88:89], v[90:91]
	s_nop 0
	v_add_f32_e32 v88, v88, v89
	ds_swizzle_b32 v89, v88 offset:swizzle(SWAP,16)
	s_waitcnt lgkmcnt(0)
	v_add_f32_e32 v88, v88, v89
	v_mov_b32_e32 v89, v88
	s_nop 1
	v_permlane32_swap_b32_e32 v88, v89
	v_add_f32_e32 v88, v88, v89
	v_max_f32_e32 v89, v95, v95
	v_max_f32_e32 v95, v89, v88
.LBB0_357:
	global_store_dwordx4 v[102:103], v[84:87], off offset:256 sc0 sc1 nt
	s_and_b64 vcc, exec, s[12:13]
	s_nop 0
	v_mov_b32_e32 v85, v76
	v_mov_b32_e32 v76, v81
	v_mov_b32_e32 v84, v80
	v_pk_mul_f32 v[80:81], v[76:77], v[168:169]
	s_nop 0
	v_pk_fma_f32 v[80:81], v[84:85], v[164:165], v[80:81] neg_lo:[0,0,1] neg_hi:[0,0,1]
	v_pk_mul_f32 v[84:85], v[84:85], v[168:169]
	s_nop 0
	v_pk_fma_f32 v[84:85], v[76:77], v[164:165], v[84:85]
	v_mov_b32_e32 v77, v78
	v_mov_b32_e32 v78, v83
	v_mov_b32_e32 v76, v82
	v_pk_mul_f32 v[82:83], v[78:79], v[162:163]
	s_nop 0
	v_pk_fma_f32 v[82:83], v[76:77], v[230:231], v[82:83] neg_lo:[0,0,1] neg_hi:[0,0,1]
	v_pk_mul_f32 v[76:77], v[76:77], v[162:163]
	s_nop 0
	v_pk_fma_f32 v[86:87], v[78:79], v[230:231], v[76:77]
	v_mul_f32_e32 v76, v186, v80
	v_mul_f32_e32 v77, v186, v84
	v_cvt_pk_bf16_f32 v76, v76, v77
	v_mul_f32_e32 v77, v186, v82
	v_mul_f32_e32 v78, v186, v86
	v_cvt_pk_bf16_f32 v77, v77, v78
	v_mul_f32_e32 v78, v186, v81
	v_mul_f32_e32 v79, v186, v85
	v_cvt_pk_bf16_f32 v78, v78, v79
	v_mul_f32_e32 v79, v186, v83
	v_mul_f32_e32 v88, v186, v87
	v_cvt_pk_bf16_f32 v79, v79, v88
	s_cbranch_vccnz .LBB0_359
	v_pk_mul_f32 v[84:85], v[84:85], v[84:85]
	v_pk_mul_f32 v[86:87], v[86:87], v[86:87]
	v_pk_fma_f32 v[80:81], v[80:81], v[80:81], v[84:85]
	v_pk_fma_f32 v[82:83], v[82:83], v[82:83], v[86:87]
	s_nop 0
	v_pk_add_f32 v[80:81], v[80:81], v[82:83]
	s_nop 0
	v_add_f32_e32 v80, v80, v81
	ds_swizzle_b32 v81, v80 offset:swizzle(SWAP,16)
	s_waitcnt lgkmcnt(0)
	v_add_f32_e32 v80, v80, v81
	v_mov_b32_e32 v81, v80
	s_nop 1
	v_permlane32_swap_b32_e32 v80, v81
	v_add_f32_e32 v80, v80, v81
	v_max_f32_e32 v81, v94, v94
	v_max_f32_e32 v94, v81, v80
.LBB0_359:
	v_ashrrev_i32_e32 v227, 31, v226
	v_lshlrev_b64 v[80:81], 9, v[226:227]
	v_lshl_add_u64 v[80:81], s[24:25], 0, v[80:81]
	v_lshl_add_u64 v[80:81], v[80:81], 0, v[2:3]
	global_store_dwordx4 v[80:81], v[76:79], off sc0 sc1 nt
	s_and_b64 vcc, exec, s[12:13]
	s_nop 0
	v_mov_b32_e32 v77, v68
	v_mov_b32_e32 v68, v73
	v_mov_b32_e32 v76, v72
	v_pk_mul_f32 v[72:73], v[68:69], v[168:169]
	s_nop 0
	v_pk_fma_f32 v[72:73], v[76:77], v[164:165], v[72:73] neg_lo:[0,0,1] neg_hi:[0,0,1]
	v_pk_mul_f32 v[76:77], v[76:77], v[168:169]
	s_nop 0
	v_pk_fma_f32 v[76:77], v[68:69], v[164:165], v[76:77]
	v_mov_b32_e32 v69, v70
	v_mov_b32_e32 v70, v75
	v_mov_b32_e32 v68, v74
	v_pk_mul_f32 v[74:75], v[70:71], v[162:163]
	s_nop 0
	v_pk_fma_f32 v[74:75], v[68:69], v[230:231], v[74:75] neg_lo:[0,0,1] neg_hi:[0,0,1]
	v_pk_mul_f32 v[68:69], v[68:69], v[162:163]
	s_nop 0
	v_pk_fma_f32 v[78:79], v[70:71], v[230:231], v[68:69]
	v_mul_f32_e32 v68, v186, v72
	v_mul_f32_e32 v69, v186, v76
	v_cvt_pk_bf16_f32 v68, v68, v69
	v_mul_f32_e32 v69, v186, v74
	v_mul_f32_e32 v70, v186, v78
	v_cvt_pk_bf16_f32 v69, v69, v70
	v_mul_f32_e32 v70, v186, v73
	v_mul_f32_e32 v71, v186, v77
	v_cvt_pk_bf16_f32 v70, v70, v71
	v_mul_f32_e32 v71, v186, v75
	v_mul_f32_e32 v82, v186, v79
	v_cvt_pk_bf16_f32 v71, v71, v82
	s_cbranch_vccnz .LBB0_361
	v_pk_mul_f32 v[76:77], v[76:77], v[76:77]
	v_pk_mul_f32 v[78:79], v[78:79], v[78:79]
	v_pk_fma_f32 v[72:73], v[72:73], v[72:73], v[76:77]
	v_pk_fma_f32 v[74:75], v[74:75], v[74:75], v[78:79]
	s_nop 0
	v_pk_add_f32 v[72:73], v[72:73], v[74:75]
	s_nop 0
	v_add_f32_e32 v72, v72, v73
	ds_swizzle_b32 v73, v72 offset:swizzle(SWAP,16)
	s_waitcnt lgkmcnt(0)
	v_add_f32_e32 v72, v72, v73
	v_mov_b32_e32 v73, v72
	s_nop 1
	v_permlane32_swap_b32_e32 v72, v73
	v_add_f32_e32 v72, v72, v73
	v_max_f32_e32 v73, v95, v95
	v_max_f32_e32 v95, v73, v72
.LBB0_361:
	global_store_dwordx4 v[80:81], v[68:71], off offset:256 sc0 sc1 nt
	s_and_b64 vcc, exec, s[12:13]
	s_nop 0
	v_mov_b32_e32 v69, v60
	v_mov_b32_e32 v60, v65
	v_mov_b32_e32 v68, v64
	v_pk_mul_f32 v[64:65], v[60:61], v[160:161]
	s_nop 0
	v_pk_fma_f32 v[64:65], v[68:69], v[156:157], v[64:65] neg_lo:[0,0,1] neg_hi:[0,0,1]
	v_pk_mul_f32 v[68:69], v[68:69], v[160:161]
	s_nop 0
	v_pk_fma_f32 v[68:69], v[60:61], v[156:157], v[68:69]
	v_mov_b32_e32 v61, v62
	v_mov_b32_e32 v62, v67
	v_mov_b32_e32 v60, v66
	v_pk_mul_f32 v[66:67], v[62:63], v[154:155]
	s_nop 0
	v_pk_fma_f32 v[66:67], v[60:61], v[190:191], v[66:67] neg_lo:[0,0,1] neg_hi:[0,0,1]
	v_pk_mul_f32 v[60:61], v[60:61], v[154:155]
	s_nop 0
	v_pk_fma_f32 v[70:71], v[62:63], v[190:191], v[60:61]
	v_mul_f32_e32 v60, v186, v64
	v_mul_f32_e32 v61, v186, v68
	v_cvt_pk_bf16_f32 v60, v60, v61
	v_mul_f32_e32 v61, v186, v66
	v_mul_f32_e32 v62, v186, v70
	v_cvt_pk_bf16_f32 v61, v61, v62
	v_mul_f32_e32 v62, v186, v65
	v_mul_f32_e32 v63, v186, v69
	v_cvt_pk_bf16_f32 v62, v62, v63
	v_mul_f32_e32 v63, v186, v67
	v_mul_f32_e32 v72, v186, v71
	v_cvt_pk_bf16_f32 v63, v63, v72
	s_cbranch_vccnz .LBB0_363
	v_pk_mul_f32 v[68:69], v[68:69], v[68:69]
	v_pk_mul_f32 v[70:71], v[70:71], v[70:71]
	v_pk_fma_f32 v[64:65], v[64:65], v[64:65], v[68:69]
	v_pk_fma_f32 v[66:67], v[66:67], v[66:67], v[70:71]
	s_nop 0
	v_pk_add_f32 v[64:65], v[64:65], v[66:67]
	s_nop 0
	v_add_f32_e32 v64, v64, v65
	ds_swizzle_b32 v65, v64 offset:swizzle(SWAP,16)
	s_waitcnt lgkmcnt(0)
	v_add_f32_e32 v64, v64, v65
	v_mov_b32_e32 v65, v64
	s_nop 1
	v_permlane32_swap_b32_e32 v64, v65
	v_add_f32_e32 v64, v64, v65
	v_max_f32_e32 v65, v94, v94
	v_max_f32_e32 v94, v65, v64
.LBB0_363:
	v_lshlrev_b64 v[64:65], 9, v[224:225]
	v_lshl_add_u64 v[64:65], s[24:25], 0, v[64:65]
	v_lshl_add_u64 v[64:65], v[64:65], 0, v[2:3]
	v_add_co_u32_e32 v66, vcc, 0x10000, v64
	s_nop 1
	v_addc_co_u32_e32 v67, vcc, 0, v65, vcc
	global_store_dwordx4 v[66:67], v[60:63], off sc0 sc1 nt
	s_and_b64 vcc, exec, s[12:13]
	s_nop 0
	v_mov_b32_e32 v61, v52
	v_mov_b32_e32 v52, v57
	v_mov_b32_e32 v60, v56
	v_pk_mul_f32 v[56:57], v[52:53], v[160:161]
	s_nop 0
	v_pk_fma_f32 v[56:57], v[60:61], v[156:157], v[56:57] neg_lo:[0,0,1] neg_hi:[0,0,1]
	v_pk_mul_f32 v[60:61], v[60:61], v[160:161]
	s_nop 0
	v_pk_fma_f32 v[60:61], v[52:53], v[156:157], v[60:61]
	v_mov_b32_e32 v53, v54
	v_mov_b32_e32 v54, v59
	v_mov_b32_e32 v52, v58
	v_pk_mul_f32 v[58:59], v[54:55], v[154:155]
	s_nop 0
	v_pk_fma_f32 v[58:59], v[52:53], v[190:191], v[58:59] neg_lo:[0,0,1] neg_hi:[0,0,1]
	v_pk_mul_f32 v[52:53], v[52:53], v[154:155]
	s_nop 0
	v_pk_fma_f32 v[62:63], v[54:55], v[190:191], v[52:53]
	v_mul_f32_e32 v52, v186, v56
	v_mul_f32_e32 v53, v186, v60
	v_cvt_pk_bf16_f32 v52, v52, v53
	v_mul_f32_e32 v53, v186, v58
	v_mul_f32_e32 v54, v186, v62
	v_cvt_pk_bf16_f32 v53, v53, v54
	v_mul_f32_e32 v54, v186, v57
	v_mul_f32_e32 v55, v186, v61
	v_cvt_pk_bf16_f32 v54, v54, v55
	v_mul_f32_e32 v55, v186, v59
	v_mul_f32_e32 v66, v186, v63
	v_cvt_pk_bf16_f32 v55, v55, v66
	s_cbranch_vccnz .LBB0_365
	v_pk_mul_f32 v[60:61], v[60:61], v[60:61]
	v_pk_mul_f32 v[62:63], v[62:63], v[62:63]
	v_pk_fma_f32 v[56:57], v[56:57], v[56:57], v[60:61]
	v_pk_fma_f32 v[58:59], v[58:59], v[58:59], v[62:63]
	s_nop 0
	v_pk_add_f32 v[56:57], v[56:57], v[58:59]
	s_nop 0
	v_add_f32_e32 v56, v56, v57
	ds_swizzle_b32 v57, v56 offset:swizzle(SWAP,16)
	s_waitcnt lgkmcnt(0)
	v_add_f32_e32 v56, v56, v57
	v_mov_b32_e32 v57, v56
	s_nop 1
	v_permlane32_swap_b32_e32 v56, v57
	v_add_f32_e32 v56, v56, v57
	v_max_f32_e32 v57, v95, v95
	v_max_f32_e32 v95, v57, v56
.LBB0_365:
	v_lshl_add_u64 v[56:57], v[64:65], 0, s[76:77]
	global_store_dwordx4 v[56:57], v[52:55], off offset:256 sc0 sc1 nt
	s_and_b64 vcc, exec, s[12:13]
	s_nop 0
	v_mov_b32_e32 v53, v44
	v_mov_b32_e32 v44, v49
	v_mov_b32_e32 v52, v48
	v_pk_mul_f32 v[48:49], v[44:45], v[152:153]
	s_nop 0
	v_pk_fma_f32 v[48:49], v[52:53], v[140:141], v[48:49] neg_lo:[0,0,1] neg_hi:[0,0,1]
	v_pk_mul_f32 v[52:53], v[52:53], v[152:153]
	s_nop 0
	v_pk_fma_f32 v[52:53], v[44:45], v[140:141], v[52:53]
	v_mov_b32_e32 v45, v46
	v_mov_b32_e32 v46, v51
	v_mov_b32_e32 v44, v50
	v_pk_mul_f32 v[50:51], v[46:47], v[134:135]
	s_nop 0
	v_pk_fma_f32 v[50:51], v[44:45], v[182:183], v[50:51] neg_lo:[0,0,1] neg_hi:[0,0,1]
	v_pk_mul_f32 v[44:45], v[44:45], v[134:135]
	s_nop 0
	v_pk_fma_f32 v[54:55], v[46:47], v[182:183], v[44:45]
	v_mul_f32_e32 v44, v186, v48
	v_mul_f32_e32 v45, v186, v52
	v_cvt_pk_bf16_f32 v44, v44, v45
	v_mul_f32_e32 v45, v186, v50
	v_mul_f32_e32 v46, v186, v54
	v_cvt_pk_bf16_f32 v45, v45, v46
	v_mul_f32_e32 v46, v186, v49
	v_mul_f32_e32 v47, v186, v53
	v_cvt_pk_bf16_f32 v46, v46, v47
	v_mul_f32_e32 v47, v186, v51
	v_mul_f32_e32 v56, v186, v55
	v_cvt_pk_bf16_f32 v47, v47, v56
	s_cbranch_vccnz .LBB0_367
	v_pk_mul_f32 v[52:53], v[52:53], v[52:53]
	v_pk_mul_f32 v[54:55], v[54:55], v[54:55]
	v_pk_fma_f32 v[48:49], v[48:49], v[48:49], v[52:53]
	v_pk_fma_f32 v[50:51], v[50:51], v[50:51], v[54:55]
	s_nop 0
	v_pk_add_f32 v[48:49], v[48:49], v[50:51]
	s_nop 0
	v_add_f32_e32 v48, v48, v49
	ds_swizzle_b32 v49, v48 offset:swizzle(SWAP,16)
	s_waitcnt lgkmcnt(0)
	v_add_f32_e32 v48, v48, v49
	v_mov_b32_e32 v49, v48
	s_nop 1
	v_permlane32_swap_b32_e32 v48, v49
	v_add_f32_e32 v48, v48, v49
	v_max_f32_e32 v49, v94, v94
	v_max_f32_e32 v94, v49, v48
.LBB0_367:
	v_lshlrev_b64 v[48:49], 9, v[224:225]
	v_lshl_add_u64 v[48:49], s[24:25], 0, v[48:49]
	v_lshl_add_u64 v[48:49], v[48:49], 0, v[2:3]
	v_add_co_u32_e32 v50, vcc, 0x12000, v48
	s_nop 1
	v_addc_co_u32_e32 v51, vcc, 0, v49, vcc
	global_store_dwordx4 v[50:51], v[44:47], off sc0 sc1 nt
	s_and_b64 vcc, exec, s[12:13]
	s_nop 0
	v_mov_b32_e32 v45, v36
	v_mov_b32_e32 v36, v41
	v_mov_b32_e32 v44, v40
	v_pk_mul_f32 v[40:41], v[36:37], v[152:153]
	s_nop 0
	v_pk_fma_f32 v[40:41], v[44:45], v[140:141], v[40:41] neg_lo:[0,0,1] neg_hi:[0,0,1]
	v_pk_mul_f32 v[44:45], v[44:45], v[152:153]
	s_nop 0
	v_pk_fma_f32 v[44:45], v[36:37], v[140:141], v[44:45]
	v_mov_b32_e32 v37, v38
	v_mov_b32_e32 v38, v43
	v_mov_b32_e32 v36, v42
	v_pk_mul_f32 v[42:43], v[38:39], v[134:135]
	s_nop 0
	v_pk_fma_f32 v[42:43], v[36:37], v[182:183], v[42:43] neg_lo:[0,0,1] neg_hi:[0,0,1]
	v_pk_mul_f32 v[36:37], v[36:37], v[134:135]
	s_nop 0
	v_pk_fma_f32 v[46:47], v[38:39], v[182:183], v[36:37]
	v_mul_f32_e32 v36, v186, v40
	v_mul_f32_e32 v37, v186, v44
	v_cvt_pk_bf16_f32 v36, v36, v37
	v_mul_f32_e32 v37, v186, v42
	v_mul_f32_e32 v38, v186, v46
	v_cvt_pk_bf16_f32 v37, v37, v38
	v_mul_f32_e32 v38, v186, v41
	v_mul_f32_e32 v39, v186, v45
	v_cvt_pk_bf16_f32 v38, v38, v39
	v_mul_f32_e32 v39, v186, v43
	v_mul_f32_e32 v50, v186, v47
	v_cvt_pk_bf16_f32 v39, v39, v50
	s_cbranch_vccnz .LBB0_369
	v_pk_mul_f32 v[44:45], v[44:45], v[44:45]
	v_pk_mul_f32 v[46:47], v[46:47], v[46:47]
	v_pk_fma_f32 v[40:41], v[40:41], v[40:41], v[44:45]
	v_pk_fma_f32 v[42:43], v[42:43], v[42:43], v[46:47]
	s_nop 0
	v_pk_add_f32 v[40:41], v[40:41], v[42:43]
	s_nop 0
	v_add_f32_e32 v40, v40, v41
	ds_swizzle_b32 v41, v40 offset:swizzle(SWAP,16)
	s_waitcnt lgkmcnt(0)
	v_add_f32_e32 v40, v40, v41
	v_mov_b32_e32 v41, v40
	s_nop 1
	v_permlane32_swap_b32_e32 v40, v41
	v_add_f32_e32 v40, v40, v41
	v_max_f32_e32 v41, v95, v95
	v_max_f32_e32 v95, v41, v40
.LBB0_369:
	s_mov_b64 s[26:27], 0x12000
	v_lshl_add_u64 v[40:41], v[48:49], 0, s[26:27]
	global_store_dwordx4 v[40:41], v[36:39], off offset:256 sc0 sc1 nt
	s_and_b64 vcc, exec, s[12:13]
	s_nop 0
	v_mov_b32_e32 v37, v28
	v_mov_b32_e32 v28, v33
	v_mov_b32_e32 v36, v32
	v_pk_mul_f32 v[32:33], v[28:29], v[132:133]
	s_nop 0
	v_pk_fma_f32 v[32:33], v[36:37], v[120:121], v[32:33] neg_lo:[0,0,1] neg_hi:[0,0,1]
	v_pk_mul_f32 v[36:37], v[36:37], v[132:133]
	s_nop 0
	v_pk_fma_f32 v[36:37], v[28:29], v[120:121], v[36:37]
	v_mov_b32_e32 v29, v30
	v_mov_b32_e32 v30, v35
	v_mov_b32_e32 v28, v34
	v_pk_mul_f32 v[34:35], v[30:31], v[174:175]
	s_nop 0
	v_pk_fma_f32 v[34:35], v[28:29], v[166:167], v[34:35] neg_lo:[0,0,1] neg_hi:[0,0,1]
	v_pk_mul_f32 v[28:29], v[28:29], v[174:175]
	s_nop 0
	v_pk_fma_f32 v[38:39], v[30:31], v[166:167], v[28:29]
	v_mul_f32_e32 v28, v186, v32
	v_mul_f32_e32 v29, v186, v36
	v_cvt_pk_bf16_f32 v28, v28, v29
	v_mul_f32_e32 v29, v186, v34
	v_mul_f32_e32 v30, v186, v38
	v_cvt_pk_bf16_f32 v29, v29, v30
	v_mul_f32_e32 v30, v186, v33
	v_mul_f32_e32 v31, v186, v37
	v_cvt_pk_bf16_f32 v30, v30, v31
	v_mul_f32_e32 v31, v186, v35
	v_mul_f32_e32 v40, v186, v39
	v_cvt_pk_bf16_f32 v31, v31, v40
	s_cbranch_vccnz .LBB0_371
	v_pk_mul_f32 v[36:37], v[36:37], v[36:37]
	v_pk_mul_f32 v[38:39], v[38:39], v[38:39]
	v_pk_fma_f32 v[32:33], v[32:33], v[32:33], v[36:37]
	v_pk_fma_f32 v[34:35], v[34:35], v[34:35], v[38:39]
	s_nop 0
	v_pk_add_f32 v[32:33], v[32:33], v[34:35]
	s_nop 0
	v_add_f32_e32 v32, v32, v33
	ds_swizzle_b32 v33, v32 offset:swizzle(SWAP,16)
	s_waitcnt lgkmcnt(0)
	v_add_f32_e32 v32, v32, v33
	v_mov_b32_e32 v33, v32
	s_nop 1
	v_permlane32_swap_b32_e32 v32, v33
	v_add_f32_e32 v32, v32, v33
	v_max_f32_e32 v33, v94, v94
	v_max_f32_e32 v94, v33, v32
.LBB0_371:
	v_lshlrev_b64 v[32:33], 9, v[224:225]
	v_lshl_add_u64 v[32:33], s[24:25], 0, v[32:33]
	v_lshl_add_u64 v[32:33], v[32:33], 0, v[2:3]
	v_add_co_u32_e32 v34, vcc, 0x14000, v32
	s_nop 1
	v_addc_co_u32_e32 v35, vcc, 0, v33, vcc
	global_store_dwordx4 v[34:35], v[28:31], off sc0 sc1 nt
	s_and_b64 vcc, exec, s[12:13]
	s_nop 0
	v_mov_b32_e32 v29, v20
	v_mov_b32_e32 v20, v25
	v_mov_b32_e32 v28, v24
	v_pk_mul_f32 v[24:25], v[20:21], v[132:133]
	s_nop 0
	v_pk_fma_f32 v[24:25], v[28:29], v[120:121], v[24:25] neg_lo:[0,0,1] neg_hi:[0,0,1]
	v_pk_mul_f32 v[28:29], v[28:29], v[132:133]
	s_nop 0
	v_pk_fma_f32 v[28:29], v[20:21], v[120:121], v[28:29]
	v_mov_b32_e32 v21, v22
	v_mov_b32_e32 v22, v27
	v_mov_b32_e32 v20, v26
	v_pk_mul_f32 v[26:27], v[22:23], v[174:175]
	s_nop 0
	v_pk_fma_f32 v[26:27], v[20:21], v[166:167], v[26:27] neg_lo:[0,0,1] neg_hi:[0,0,1]
	v_pk_mul_f32 v[20:21], v[20:21], v[174:175]
	s_nop 0
	v_pk_fma_f32 v[30:31], v[22:23], v[166:167], v[20:21]
	v_mul_f32_e32 v20, v186, v24
	v_mul_f32_e32 v21, v186, v28
	v_cvt_pk_bf16_f32 v20, v20, v21
	v_mul_f32_e32 v21, v186, v26
	v_mul_f32_e32 v22, v186, v30
	v_cvt_pk_bf16_f32 v21, v21, v22
	v_mul_f32_e32 v22, v186, v25
	v_mul_f32_e32 v23, v186, v29
	v_cvt_pk_bf16_f32 v22, v22, v23
	v_mul_f32_e32 v23, v186, v27
	v_mul_f32_e32 v34, v186, v31
	v_cvt_pk_bf16_f32 v23, v23, v34
	s_cbranch_vccnz .LBB0_373
	v_pk_mul_f32 v[28:29], v[28:29], v[28:29]
	v_pk_mul_f32 v[30:31], v[30:31], v[30:31]
	v_pk_fma_f32 v[24:25], v[24:25], v[24:25], v[28:29]
	v_pk_fma_f32 v[26:27], v[26:27], v[26:27], v[30:31]
	s_nop 0
	v_pk_add_f32 v[24:25], v[24:25], v[26:27]
	s_nop 0
	v_add_f32_e32 v24, v24, v25
	ds_swizzle_b32 v25, v24 offset:swizzle(SWAP,16)
	s_waitcnt lgkmcnt(0)
	v_add_f32_e32 v24, v24, v25
	v_mov_b32_e32 v25, v24
	s_nop 1
	v_permlane32_swap_b32_e32 v24, v25
	v_add_f32_e32 v24, v24, v25
	v_max_f32_e32 v25, v95, v95
	v_max_f32_e32 v95, v25, v24
.LBB0_373:
	s_mov_b64 s[26:27], 0x14000
	v_lshl_add_u64 v[24:25], v[32:33], 0, s[26:27]
	global_store_dwordx4 v[24:25], v[20:23], off offset:256 sc0 sc1 nt
	s_and_b64 vcc, exec, s[12:13]
	s_nop 0
	v_mov_b32_e32 v21, v12
	v_mov_b32_e32 v12, v17
	v_mov_b32_e32 v20, v16
	v_pk_mul_f32 v[16:17], v[12:13], v[96:97]
	s_nop 0
	v_pk_fma_f32 v[16:17], v[20:21], v[92:93], v[16:17] neg_lo:[0,0,1] neg_hi:[0,0,1]
	v_pk_mul_f32 v[20:21], v[20:21], v[96:97]
	s_nop 0
	v_pk_fma_f32 v[20:21], v[12:13], v[92:93], v[20:21]
	v_mov_b32_e32 v13, v14
	v_mov_b32_e32 v14, v19
	v_mov_b32_e32 v12, v18
	v_pk_mul_f32 v[18:19], v[14:15], v[158:159]
	s_nop 0
	v_pk_fma_f32 v[18:19], v[12:13], v[122:123], v[18:19] neg_lo:[0,0,1] neg_hi:[0,0,1]
	v_pk_mul_f32 v[12:13], v[12:13], v[158:159]
	s_nop 0
	v_pk_fma_f32 v[22:23], v[14:15], v[122:123], v[12:13]
	v_mul_f32_e32 v12, v186, v16
	v_mul_f32_e32 v13, v186, v20
	v_cvt_pk_bf16_f32 v12, v12, v13
	v_mul_f32_e32 v13, v186, v18
	v_mul_f32_e32 v14, v186, v22
	v_cvt_pk_bf16_f32 v13, v13, v14
	v_mul_f32_e32 v14, v186, v17
	v_mul_f32_e32 v15, v186, v21
	v_cvt_pk_bf16_f32 v14, v14, v15
	v_mul_f32_e32 v15, v186, v19
	v_mul_f32_e32 v24, v186, v23
	v_cvt_pk_bf16_f32 v15, v15, v24
	s_cbranch_vccnz .LBB0_375
	v_pk_mul_f32 v[20:21], v[20:21], v[20:21]
	v_pk_mul_f32 v[22:23], v[22:23], v[22:23]
	v_pk_fma_f32 v[16:17], v[16:17], v[16:17], v[20:21]
	v_pk_fma_f32 v[18:19], v[18:19], v[18:19], v[22:23]
	s_nop 0
	v_pk_add_f32 v[16:17], v[16:17], v[18:19]
	s_nop 0
	v_add_f32_e32 v16, v16, v17
	ds_swizzle_b32 v17, v16 offset:swizzle(SWAP,16)
	s_waitcnt lgkmcnt(0)
	v_add_f32_e32 v16, v16, v17
	v_mov_b32_e32 v17, v16
	s_nop 1
	v_permlane32_swap_b32_e32 v16, v17
	v_add_f32_e32 v16, v16, v17
	v_max_f32_e32 v17, v94, v94
	v_max_f32_e32 v94, v17, v16
.LBB0_375:
	v_lshlrev_b64 v[16:17], 9, v[224:225]
	v_lshl_add_u64 v[16:17], s[24:25], 0, v[16:17]
	v_lshl_add_u64 v[18:19], v[16:17], 0, v[2:3]
	s_mov_b64 s[12:13], 0x16000
	v_lshl_add_u64 v[16:17], v[18:19], 0, s[12:13]
	v_add_co_u32_e32 v18, vcc, 0x16000, v18
	v_mul_f32_e32 v2, v9, v96
	s_nop 0
	v_addc_co_u32_e32 v19, vcc, 0, v19, vcc
	global_store_dwordx4 v[18:19], v[12:15], off sc0 sc1 nt
	v_mov_b32_e32 v18, v158
	v_mov_b32_e32 v19, v122
	v_mov_b32_e32 v12, v92
	v_mov_b32_e32 v13, v96
	v_pk_fma_f32 v[12:13], v[8:9], v[12:13], v[2:3] op_sel_hi:[1,1,0] neg_lo:[0,0,1] neg_hi:[0,0,1]
	v_mov_b32_e32 v14, v96
	v_mov_b32_e32 v15, v92
	v_mul_f32_e32 v2, v9, v92
	v_pk_fma_f32 v[8:9], v[8:9], v[14:15], v[2:3] op_sel_hi:[1,1,0]
	v_mov_b32_e32 v14, v122
	v_mov_b32_e32 v15, v158
	v_mul_f32_e32 v2, v11, v158
	v_pk_fma_f32 v[14:15], v[10:11], v[14:15], v[2:3] op_sel_hi:[1,1,0] neg_lo:[0,0,1] neg_hi:[0,0,1]
	v_mul_f32_e32 v2, v11, v122
	v_pk_fma_f32 v[10:11], v[10:11], v[18:19], v[2:3] op_sel_hi:[1,1,0]
	v_mov_b32_e32 v96, v93
	v_mul_f32_e32 v2, v5, v97
	v_pk_fma_f32 v[18:19], v[4:5], v[96:97], v[2:3] op_sel_hi:[1,1,0] neg_lo:[0,0,1] neg_hi:[0,0,1]
	v_mov_b32_e32 v92, v97
	v_mul_f32_e32 v2, v5, v93
	v_pk_fma_f32 v[20:21], v[4:5], v[92:93], v[2:3] op_sel_hi:[1,1,0]
	v_mov_b32_e32 v158, v123
	v_mul_f32_e32 v2, v7, v159
	v_pk_fma_f32 v[22:23], v[6:7], v[158:159], v[2:3] op_sel_hi:[1,1,0] neg_lo:[0,0,1] neg_hi:[0,0,1]
	v_mov_b32_e32 v122, v159
	v_mul_f32_e32 v2, v7, v123
	v_pk_fma_f32 v[24:25], v[6:7], v[122:123], v[2:3] op_sel_hi:[1,1,0]
	v_mul_f32_e32 v2, v186, v12
	v_mul_f32_e32 v4, v186, v8
	v_cvt_pk_bf16_f32 v4, v2, v4
	v_mul_f32_e32 v2, v186, v14
	v_mul_f32_e32 v5, v186, v10
	v_cvt_pk_bf16_f32 v5, v2, v5
	v_mul_f32_e32 v2, v186, v18
	v_mul_f32_e32 v6, v186, v20
	v_mul_f32_e32 v7, v186, v24
	s_mov_b64 s[12:13], -1
	s_and_b64 vcc, exec, s[22:23]
	v_cvt_pk_bf16_f32 v6, v2, v6
	v_mul_f32_e32 v2, v186, v22
	v_cvt_pk_bf16_f32 v7, v2, v7
	s_cbranch_vccnz .LBB0_378
	s_andn2_b64 vcc, exec, s[12:13]
	s_cbranch_vccz .LBB0_379

.LBB0_378:
	global_store_dwordx4 v[16:17], v[4:7], off offset:256 sc0 sc1 nt
	s_cbranch_execnz .LBB0_377
.LBB0_379:
	v_mul_f32_e32 v2, v22, v22
	v_mul_f32_e32 v9, v18, v18
	v_fmac_f32_e32 v2, v24, v24
	v_fmac_f32_e32 v9, v20, v20
	global_store_dwordx4 v[16:17], v[4:7], off offset:256 sc0 sc1 nt
	v_add_f32_e32 v2, v9, v2
	v_mul_f32_e32 v9, v14, v14
	v_and_b32_e32 v5, 64, v1
	v_xor_b32_e32 v4, 1, v1
	v_add_u32_e32 v7, 64, v5
	v_fmac_f32_e32 v9, v10, v10
	v_mul_f32_e32 v10, v12, v12
	v_cmp_lt_i32_e32 vcc, v4, v7
	v_xor_b32_e32 v5, 2, v1
	v_fmac_f32_e32 v10, v8, v8
	v_cndmask_b32_e32 v4, v1, v4, vcc
	v_cmp_lt_i32_e32 vcc, v5, v7
	v_xor_b32_e32 v6, 4, v1
	v_add_f32_e32 v8, v10, v9
	v_cndmask_b32_e32 v5, v1, v5, vcc
	v_cmp_lt_i32_e32 vcc, v6, v7
	v_xor_b32_e32 v9, 8, v1
	v_lshlrev_b32_e32 v4, 2, v4
	v_cndmask_b32_e32 v6, v1, v6, vcc
	v_cmp_lt_i32_e32 vcc, v9, v7
	v_max_f32_e32 v10, v94, v94
	v_lshlrev_b32_e32 v5, 2, v5
	v_cndmask_b32_e32 v7, v1, v9, vcc
	ds_bpermute_b32 v9, v4, v94
	v_lshlrev_b32_e32 v6, 2, v6
	v_add_f32_e32 v2, v8, v2
	ds_swizzle_b32 v8, v2 offset:swizzle(SWAP,16)
	s_addk_i32 s5, 0x8000
	s_waitcnt lgkmcnt(0)
	v_max_f32_e32 v9, v9, v9
	v_max_f32_e32 v9, v10, v9
	ds_bpermute_b32 v10, v5, v9
	v_lshlrev_b32_e32 v7, 2, v7
	s_lshr_b32 s5, s5, 14
	s_add_i32 s5, s5, 8
	s_lshr_b32 s7, s18, 4
	s_waitcnt lgkmcnt(0)
	v_max_f32_e32 v10, v10, v10
	v_max_f32_e32 v9, v9, v10
	ds_bpermute_b32 v10, v6, v9
	v_add_f32_e32 v2, v2, v8
	s_cmpk_gt_i32 s18, 0x7f
	v_mov_b32_e32 v8, v2
	s_cselect_b32 s7, s5, s7
	s_waitcnt lgkmcnt(0)
	v_max_f32_e32 v10, v10, v10
	v_max_f32_e32 v9, v9, v10
	ds_bpermute_b32 v10, v7, v9
	v_permlane32_swap_b32_e32 v2, v8
	s_lshl_b32 s5, s14, 3
	s_lshl_b32 s7, s7, 5
	s_and_saveexec_b64 s[12:13], s[8:9]
	s_cbranch_execz .LBB0_384
	s_waitcnt lgkmcnt(0)
	v_max_f32_e32 v10, v10, v10
	v_max_f32_e32 v9, v9, v9
	s_mov_b64 s[14:15], exec
	v_max_f32_e32 v9, v9, v10
	s_mov_b32 s18, 0
